# v74 + placement-check loads issued after the first barrier and consumed at the next barrier's entry (latency hidden behind P1)
# speedup vs baseline: 1.0074x; 1.0074x over previous
.LBB0_217:
	s_or_b64 exec, exec, s[4:5]
	s_cmpk_lt_i32 s2, 0x300
	s_cselect_b64 s[6:7], -1, 0
	s_mov_b64 s[4:5], s[0:1]
	s_waitcnt vmcnt(14)
	v_mov_b32_e32 v8, v192
	s_waitcnt lgkmcnt(0)
	s_barrier
	s_load_dwordx2 s[98:99], s[0:1], 0x80
	v_and_b32_e32 v253, 7, v192
	v_lshlrev_b32_e32 v253, 8, v253
	s_waitcnt lgkmcnt(0)
	global_load_dword v254, v253, s[98:99] sc1
	global_load_dword v255, v253, s[98:99] offset:2048 sc1
	s_ashr_i32 s47, s52, 31
	s_ashr_i32 s76, s2, 31
	v_writelane_b32 v250, s6, 0
	v_readfirstlane_b32 s13, v8
	s_and_b64 vcc, exec, s[6:7]
	v_writelane_b32 v250, s7, 1
	s_cbranch_vccz .LBB0_233
	v_lshlrev_b32_e32 v0, 4, v8
	v_add_u32_e32 v1, 0x2000, v0
	v_ashrrev_i32_e32 v2, 31, v1
	v_lshrrev_b32_e32 v2, 22, v2
	v_add_u32_e32 v2, v1, v2
	v_ashrrev_i32_e32 v9, 10, v2
	v_mul_i32_i24_e32 v2, 0x400, v9
	v_sub_u32_e32 v1, v1, v2
	v_lshrrev_b32_e32 v2, 4, v1
	v_bitop3_b32 v1, v2, v1, 32 bitop3:0x6c
	v_ashrrev_i32_e32 v2, 31, v1
	v_lshrrev_b32_e32 v2, 26, v2
	v_add_u32_e32 v2, v1, v2
	v_lshlrev_b32_e32 v3, 3, v9
	s_waitcnt vmcnt(13)
	v_ashrrev_i32_e32 v10, 6, v2
	v_and_b32_e32 v3, -16, v3
	v_add_u32_e32 v3, v10, v3
	v_and_b32_e32 v4, 3, v10
	s_mov_b32 s6, 0xfffe0
	v_lshrrev_b32_e32 v5, 2, v3
	v_lshlrev_b32_e32 v6, 1, v3
	v_and_b32_e32 v2, 0xc0, v2
	v_and_or_b32 v4, v3, s6, v4
	v_and_b32_e32 v5, 4, v5
	v_and_b32_e32 v6, 24, v6
	v_sub_u32_e32 v1, v1, v2
	v_mov_b32_e32 v2, 1
	v_or3_b32 v4, v4, v5, v6
	v_lshlrev_b32_e32 v5, 5, v9
	v_ashrrev_i16_sdwa v1, v2, sext(v1) dst_sel:DWORD dst_unused:UNUSED_PAD src0_sel:DWORD src1_sel:BYTE_0
	v_and_b32_e32 v5, 32, v5
	v_bfe_i32 v11, v1, 0, 16
	v_add_lshl_u32 v1, v5, v11, 1
	v_lshl_add_u32 v128, v4, 12, v1
	v_lshl_add_u32 v130, v3, 12, v1
	v_bfe_i32 v1, v8, 27, 1
	v_lshrrev_b32_e32 v1, 22, v1
	v_add_u32_e32 v1, v0, v1
	v_and_b32_e32 v1, 0xfffffc00, v1
	s_load_dwordx2 s[4:5], s[4:5], 0x80
	v_sub_u32_e32 v0, v0, v1
	v_lshrrev_b32_e32 v1, 4, v0
	v_ashrrev_i32_e32 v3, 31, v8
	v_bitop3_b32 v0, v1, v0, 32 bitop3:0x6c
	v_lshrrev_b32_e32 v3, 26, v3
	v_ashrrev_i32_e32 v1, 31, v0
	v_add_u32_e32 v3, v8, v3
	v_lshrrev_b32_e32 v1, 26, v1
	v_ashrrev_i32_e32 v13, 6, v3
	s_waitcnt lgkmcnt(0)
	s_add_u32 s30, s4, 0xc600000
	v_add_u32_e32 v1, v0, v1
	v_lshlrev_b32_e32 v3, 3, v13
	s_addc_u32 s31, s5, 0
	v_ashrrev_i32_e32 v12, 6, v1
	v_and_b32_e32 v3, -16, v3
	s_add_u32 s34, s4, 0x100000
	v_add_u32_e32 v3, v12, v3
	v_and_b32_e32 v4, 3, v12
	s_addc_u32 s35, s5, 0
	v_and_or_b32 v4, v3, s6, v4
	s_lshr_b32 s6, s76, 29
	s_add_i32 s6, s2, s6
	s_ashr_i32 s10, s13, 6
	s_ashr_i32 s7, s6, 3
	s_and_b32 s6, s6, -8
	s_ashr_i32 s14, s13, 8
	s_lshl_b32 s36, s10, 10
	s_sub_i32 s6, s2, s6
	s_cmp_lt_i32 s6, 0
	s_movk_i32 s37, 0x61
	s_cselect_b32 s8, s37, 0x60
	s_mul_i32 s6, s6, s8
	s_add_i32 s6, s6, s7
	s_mul_hi_i32 s7, s6, 0x2aaaaaab
	s_lshr_b32 s8, s7, 31
	s_ashr_i32 s7, s7, 4
	s_add_i32 s7, s7, s8
	s_lshl_b32 s8, s7, 2
	s_mulk_i32 s7, 0x60
	s_sub_i32 s6, s6, s7
	s_bfe_i32 s7, s6, 0x80000
	s_bfe_u32 s7, s7, 0x2000d
	s_add_i32 s7, s6, s7
	s_bfe_i32 s9, s7, 0x80000
	s_and_b32 s7, s7, 0xfc
	s_sub_i32 s6, s6, s7
	s_sext_i32_i16 s9, s9
	s_sext_i32_i8 s6, s6
	v_lshrrev_b32_e32 v5, 2, v3
	v_lshlrev_b32_e32 v6, 1, v3
	v_and_b32_e32 v1, 0xc0, v1
	s_lshr_b32 s12, s9, 2
	s_add_i32 s22, s8, s6
	v_and_b32_e32 v5, 4, v5
	v_and_b32_e32 v6, 24, v6
	v_sub_u32_e32 v0, v0, v1
	s_ashr_i32 s23, s22, 31
	s_bfe_i64 s[8:9], s[12:13], 0x100000
	v_or3_b32 v4, v4, v5, v6
	v_lshlrev_b32_e32 v5, 5, v13
	v_ashrrev_i16_sdwa v0, v2, sext(v0) dst_sel:DWORD dst_unused:UNUSED_PAD src0_sel:DWORD src1_sel:BYTE_0
	s_lshl_b64 s[6:7], s[22:23], 20
	s_lshl_b64 s[8:9], s[8:9], 20
	v_and_b32_e32 v5, 32, v5
	s_waitcnt vmcnt(12)
	v_bfe_i32 v14, v0, 0, 16
	s_add_u32 s26, s34, s8
	v_add_lshl_u32 v0, v5, v14, 1
	s_addc_u32 s27, s35, s9
	s_add_i32 s23, s36, 0
	v_lshl_add_u32 v132, v4, 12, v0
	s_add_i32 m0, s23, 0x10000
	v_lshl_add_u32 v134, v3, 12, v0
	global_load_lds_dwordx4 v132, s[26:27]
	s_add_i32 m0, s23, 0x12000
	s_add_u32 s8, s26, 0x80000
	global_load_lds_dwordx4 v128, s[26:27]
	s_addc_u32 s9, s27, 0
	s_add_i32 m0, s23, 0x14000
	v_mov_b32_e32 v133, 0
	global_load_lds_dwordx4 v132, s[8:9]
	s_add_i32 m0, s23, 0x16000
	s_add_u32 s24, s30, s6
	s_addc_u32 s25, s31, s7
	s_add_i32 s38, s23, 0x2000
	global_load_lds_dwordx4 v128, s[8:9]
	s_mov_b32 m0, s23
	s_add_u32 s6, s24, 0x80000
	global_load_lds_dwordx4 v134, s[24:25]
	s_mov_b32 m0, s38
	s_addc_u32 s7, s25, 0
	s_add_i32 s39, s23, 0x4000
	global_load_lds_dwordx4 v130, s[24:25]
	s_mov_b32 m0, s39
	s_add_i32 s40, s23, 0x6000
	global_load_lds_dwordx4 v134, s[6:7]
	s_mov_b32 m0, s40
	v_mov_b32_e32 v129, v133
	global_load_lds_dwordx4 v130, s[6:7]
	v_mov_b32_e32 v135, v133
	v_mov_b32_e32 v131, v133
	s_cmp_eq_u32 s14, 1
	s_mov_b32 s41, 0
	v_lshl_add_u64 v[6:7], s[26:27], 0, v[132:133]
	v_lshl_add_u64 v[4:5], s[26:27], 0, v[128:129]
	v_lshl_add_u64 v[0:1], s[24:25], 0, v[134:135]
	s_cselect_b64 s[6:7], -1, 0
	s_cmp_lg_u32 s14, 1
	v_lshl_add_u64 v[2:3], s[24:25], 0, v[130:131]
	s_cbranch_scc1 .LBB0_220
	s_barrier

.LBB0_233:
	s_mov_b64 s[6:7], s[0:1]
	s_getreg_b32 s8, hwreg(HW_REG_XCC_ID, 0, 4)
	s_waitcnt vmcnt(0)
	s_waitcnt vmcnt(0)
	v_add_u32_e32 v254, v254, v255
	v_cmp_ne_u32_e32 vcc, 17, v254
	s_nop 3
	s_cmp_eq_u64 vcc, 0
	s_cselect_b32 s99, 1, 0
	s_cmpk_lg_i32 s52, 0x100
	s_cselect_b32 s99, 0, s99
	s_barrier
	s_and_saveexec_b64 s[4:5], s[44:45]
	s_xor_b64 s[4:5], exec, s[4:5]
	s_cbranch_execz .LBB0_286
	s_add_i32 s9, 0, 0x23fe0
	v_mov_b32_e32 v0, s9
	s_load_dwordx2 s[6:7], s[6:7], 0x80
	s_waitcnt vmcnt(0) expcnt(0) lgkmcnt(0)
	ds_read_b32 v2, v0
	s_add_i32 s9, 0, 0x23fe4
	v_mov_b32_e32 v0, s9
	ds_read_b32 v0, v0
	s_and_b32 s33, s8, 15
	s_waitcnt lgkmcnt(1)
	v_cmp_ne_u32_e32 vcc, 0, v2
	s_cbranch_vccnz .LBB0_249
	s_load_dword s8, s[0:1], 0x90
	s_mov_b32 s59, 1
	v_mov_b32_e32 v16, 0
	s_waitcnt lgkmcnt(0)
	s_mul_i32 s58, s53, s8
	s_add_u32 s8, s6, 0x4200
	s_addc_u32 s9, s7, 0
	s_add_u32 s10, s6, 0x4400
	s_addc_u32 s11, s7, 0
	s_add_u32 s12, s6, 0x4500
	s_addc_u32 s13, s7, 0
	s_add_u32 s14, s6, 0x4600
	s_addc_u32 s15, s7, 0
	s_add_u32 s16, s6, 0x4700
	s_addc_u32 s17, s7, 0
	s_add_u32 s18, s6, 0x4800
	s_addc_u32 s19, s7, 0
	s_add_u32 s20, s6, 0x4900
	s_addc_u32 s21, s7, 0
	s_add_u32 s22, s6, 0x4a00
	s_addc_u32 s23, s7, 0
	s_add_u32 s24, s6, 0x4b00
	s_addc_u32 s25, s7, 0
	s_add_u32 s26, s6, 0x4c00
	s_addc_u32 s27, s7, 0
	s_add_u32 s28, s6, 0x4d00
	s_addc_u32 s29, s7, 0
	s_add_u32 s30, s6, 0x4e00
	s_addc_u32 s31, s7, 0
	s_add_u32 s34, s6, 0x4f00
	s_addc_u32 s35, s7, 0
	s_add_u32 s36, s6, 0x5000
	s_addc_u32 s37, s7, 0
	s_add_u32 s38, s6, 0x5100
	s_addc_u32 s39, s7, 0
	s_add_u32 s40, s6, 0x5200
	s_addc_u32 s41, s7, 0
	s_add_u32 s42, s6, 0x5300
	s_mul_i32 s58, s58, s52
	s_addc_u32 s43, s7, 0
	s_branch .LBB0_237
